# P7 SwiGLU epilogue rewritten by hand with packed f32 math (fewer VALU ops)
# speedup vs baseline: 1.0086x; 1.0086x over previous
; __device__ __forceinline__ unsigned cvt_pk(float lo, float hi) { unsigned r; asm volatile("v_cvt_pk_bf16_f32 %0, %1, %2" : "=v"(r) : "v"(lo), "v"(hi)); return r; }
; __device__ __forceinline__ float fast_sigmoid(float v) { return __builtin_amdgcn_rcpf(1.0f + __builtin_amdgcn_exp2f(-1.4426950408889634f * v)); }
;     __device__ __forceinline__ void operator()(const pg8::f32x4 (&acc)[2][2][4][2], const pg8::Unit& u, int wr, int wc, int fr, int fq) const {
;         const int row0 = u.pm * 256 + wr * 64 + fr, col0 = u.pn * 128 + wc * 32 + 8 * fq;
;         float rsv[8];
; #pragma unroll
;         for (int q = 0; q < 8; ++q) rsv[q] = rowss[row0 + (q >> 2) * 128 + (q & 3) * 16];
;         asm volatile("" : "+v"(rsv[0]), "+v"(rsv[1]), "+v"(rsv[2]), "+v"(rsv[3]), "+v"(rsv[4]), "+v"(rsv[5]), "+v"(rsv[6]), "+v"(rsv[7]));
; #pragma unroll
;         for (int ai = 0; ai < 2; ++ai)
; #pragma unroll
;             for (int m = 0; m < 4; ++m) { const int row = row0 + ai * 128 + m * 16; const float rs = __builtin_amdgcn_rsqf(rsv[ai * 4 + m] * (1.0f / DM) + EPS); float o[8];
; #pragma unroll
;                 for (int n = 0; n < 2; ++n)
; #pragma unroll
;                     for (int e = 0; e < 4; ++e) { const float g = acc[ai][0][m][n][e] * rs, up = acc[ai][1][m][n][e] * rs; o[n * 4 + e] = g * fast_sigmoid(g) * up; }
;                 u32x4 w; w.x = cvt_pk(o[0], o[1]); w.y = cvt_pk(o[2], o[3]); w.z = cvt_pk(o[4], o[5]); w.w = cvt_pk(o[6], o[7]);
;                 *(u32x4*)(O + (size_t)row * ldc + col0) = w; }
.LBB0_669:
	v_lshl_add_u32 v136, s24, 8, v138
	v_ashrrev_i32_e32 v137, 31, v136
	v_lshl_add_u64 v[148:149], v[136:137], 2, s[10:11]
	global_load_dword v170, v[148:149], off
	global_load_dword v171, v[148:149], off offset:64
	global_load_dword v172, v[148:149], off offset:128
	global_load_dword v173, v[148:149], off offset:192
	global_load_dword v174, v[148:149], off offset:512
	global_load_dword v175, v[148:149], off offset:576
	global_load_dword v176, v[148:149], off offset:640
	global_load_dword v177, v[148:149], off offset:704
	v_pk_mul_f32 v[124:125], v[116:117], v[124:125]
	v_pk_mul_f32 v[126:127], v[118:119], v[126:127]
	v_pk_mul_f32 v[120:121], v[112:113], v[120:121]
	v_pk_mul_f32 v[122:123], v[114:115], v[122:123]
	v_pk_mul_f32 v[104:105], v[108:109], v[104:105]
	v_pk_mul_f32 v[106:107], v[110:111], v[106:107]
	v_pk_mul_f32 v[96:97], v[100:101], v[96:97]
	v_pk_mul_f32 v[98:99], v[102:103], v[98:99]
	v_pk_mul_f32 v[88:89], v[92:93], v[88:89]
	v_pk_mul_f32 v[90:91], v[94:95], v[90:91]
	v_pk_mul_f32 v[80:81], v[84:85], v[80:81]
	v_pk_mul_f32 v[82:83], v[86:87], v[82:83]
	v_pk_mul_f32 v[72:73], v[76:77], v[72:73]
	v_pk_mul_f32 v[74:75], v[78:79], v[74:75]
	v_pk_mul_f32 v[64:65], v[68:69], v[64:65]
	v_pk_mul_f32 v[66:67], v[70:71], v[66:67]
	v_pk_mul_f32 v[56:57], v[60:61], v[56:57]
	v_pk_mul_f32 v[58:59], v[62:63], v[58:59]
	v_pk_mul_f32 v[48:49], v[52:53], v[48:49]
	v_pk_mul_f32 v[50:51], v[54:55], v[50:51]
	v_pk_mul_f32 v[40:41], v[44:45], v[40:41]
	v_pk_mul_f32 v[42:43], v[46:47], v[42:43]
	v_pk_mul_f32 v[32:33], v[36:37], v[32:33]
	v_pk_mul_f32 v[34:35], v[38:39], v[34:35]
	v_pk_mul_f32 v[24:25], v[28:29], v[24:25]
	v_pk_mul_f32 v[26:27], v[30:31], v[26:27]
	v_pk_mul_f32 v[16:17], v[20:21], v[16:17]
	v_pk_mul_f32 v[18:19], v[22:23], v[18:19]
	v_pk_mul_f32 v[8:9], v[12:13], v[8:9]
	v_pk_mul_f32 v[10:11], v[14:15], v[10:11]
	v_pk_mul_f32 v[0:1], v[4:5], v[0:1]
	v_pk_mul_f32 v[2:3], v[6:7], v[2:3]
	v_lshl_or_b32 v150, s51, 7, v140
	v_ashrrev_i32_e32 v151, 31, v150
	v_mov_b64_e32 v[154:155], s[48:49]
	v_mad_i64_i32 v[152:153], s[26:27], v136, s50, v[154:155]
	v_lshlrev_b64 v[150:151], 1, v[150:151]
	s_lshl_b32 s60, s50, 4
	s_mov_b32 s61, 0
	s_mul_i32 s62, s50, 0x50
	s_mov_b32 s63, 0
	v_lshl_add_u64 v[152:153], v[152:153], 0, v[150:151]
	s_waitcnt vmcnt(0)
	v_fmamk_f32 v180, v170, 0x3a800000, v144
	v_fmamk_f32 v184, v171, 0x3a800000, v144
	v_fmamk_f32 v188, v172, 0x3a800000, v144
	v_fmamk_f32 v192, v173, 0x3a800000, v144
	v_fmamk_f32 v196, v174, 0x3a800000, v144
	v_fmamk_f32 v200, v175, 0x3a800000, v144
	v_fmamk_f32 v204, v176, 0x3a800000, v144
	v_fmamk_f32 v208, v177, 0x3a800000, v144
	v_rsq_f32_e32 v182, v180
	v_rsq_f32_e32 v186, v184
	v_rsq_f32_e32 v190, v188
	v_rsq_f32_e32 v194, v192
	v_rsq_f32_e32 v198, v196
	v_rsq_f32_e32 v202, v200
	v_rsq_f32_e32 v206, v204
	v_rsq_f32_e32 v210, v208
	s_nop 0
	v_mul_f32_e32 v182, 0xbfb8aa3b, v182
	v_mul_f32_e32 v186, 0xbfb8aa3b, v186
	v_mul_f32_e32 v190, 0xbfb8aa3b, v190
	v_mul_f32_e32 v194, 0xbfb8aa3b, v194
	v_mul_f32_e32 v198, 0xbfb8aa3b, v198
	v_mul_f32_e32 v202, 0xbfb8aa3b, v202
	v_mul_f32_e32 v206, 0xbfb8aa3b, v206
	v_mul_f32_e32 v210, 0xbfb8aa3b, v210
	v_pk_mul_f32 v[116:117], v[116:117], v[182:183] op_sel_hi:[1,0]
	v_pk_mul_f32 v[118:119], v[118:119], v[182:183] op_sel_hi:[1,0]
	v_pk_mul_f32 v[112:113], v[112:113], v[182:183] op_sel_hi:[1,0]
	v_pk_mul_f32 v[114:115], v[114:115], v[182:183] op_sel_hi:[1,0]
	v_exp_f32_e32 v116, v116
	v_exp_f32_e32 v117, v117
	v_exp_f32_e32 v118, v118
	v_exp_f32_e32 v119, v119
	v_exp_f32_e32 v112, v112
	v_exp_f32_e32 v113, v113
	v_exp_f32_e32 v114, v114
	v_exp_f32_e32 v115, v115
	v_pk_fma_f32 v[116:117], v[116:117], v[180:181], v[180:181] op_sel_hi:[1,0,0]
	v_pk_fma_f32 v[118:119], v[118:119], v[180:181], v[180:181] op_sel_hi:[1,0,0]
	v_pk_fma_f32 v[112:113], v[112:113], v[180:181], v[180:181] op_sel_hi:[1,0,0]
	v_pk_fma_f32 v[114:115], v[114:115], v[180:181], v[180:181] op_sel_hi:[1,0,0]
	v_rcp_f32_e32 v116, v116
	v_rcp_f32_e32 v117, v117
	v_rcp_f32_e32 v118, v118
	v_rcp_f32_e32 v119, v119
	v_rcp_f32_e32 v112, v112
	v_rcp_f32_e32 v113, v113
	v_rcp_f32_e32 v114, v114
	v_rcp_f32_e32 v115, v115
	v_pk_mul_f32 v[124:125], v[124:125], v[116:117]
	v_pk_mul_f32 v[126:127], v[126:127], v[118:119]
	v_pk_mul_f32 v[120:121], v[120:121], v[112:113]
	v_pk_mul_f32 v[122:123], v[122:123], v[114:115]
	v_cvt_pk_bf16_f32 v116, v124, v125
	v_cvt_pk_bf16_f32 v117, v126, v127
	v_cvt_pk_bf16_f32 v118, v120, v121
	v_cvt_pk_bf16_f32 v119, v122, v123
	global_store_dwordx4 v[152:153], v[116:119], off
	v_pk_mul_f32 v[108:109], v[108:109], v[186:187] op_sel_hi:[1,0]
	v_pk_mul_f32 v[110:111], v[110:111], v[186:187] op_sel_hi:[1,0]
	v_pk_mul_f32 v[100:101], v[100:101], v[186:187] op_sel_hi:[1,0]
	v_pk_mul_f32 v[102:103], v[102:103], v[186:187] op_sel_hi:[1,0]
	v_exp_f32_e32 v108, v108
	v_exp_f32_e32 v109, v109
	v_exp_f32_e32 v110, v110
	v_exp_f32_e32 v111, v111
	v_exp_f32_e32 v100, v100
	v_exp_f32_e32 v101, v101
	v_exp_f32_e32 v102, v102
	v_exp_f32_e32 v103, v103
	v_pk_fma_f32 v[108:109], v[108:109], v[184:185], v[184:185] op_sel_hi:[1,0,0]
	v_pk_fma_f32 v[110:111], v[110:111], v[184:185], v[184:185] op_sel_hi:[1,0,0]
	v_pk_fma_f32 v[100:101], v[100:101], v[184:185], v[184:185] op_sel_hi:[1,0,0]
	v_pk_fma_f32 v[102:103], v[102:103], v[184:185], v[184:185] op_sel_hi:[1,0,0]
	v_rcp_f32_e32 v108, v108
	v_rcp_f32_e32 v109, v109
	v_rcp_f32_e32 v110, v110
	v_rcp_f32_e32 v111, v111
	v_rcp_f32_e32 v100, v100
	v_rcp_f32_e32 v101, v101
	v_rcp_f32_e32 v102, v102
	v_rcp_f32_e32 v103, v103
	v_pk_mul_f32 v[104:105], v[104:105], v[108:109]
	v_pk_mul_f32 v[106:107], v[106:107], v[110:111]
; __device__ __forceinline__ unsigned cvt_pk(float lo, float hi) { unsigned r; asm volatile("v_cvt_pk_bf16_f32 %0, %1, %2" : "=v"(r) : "v"(lo), "v"(hi)); return r; }
; __device__ __forceinline__ float fast_sigmoid(float v) { return __builtin_amdgcn_rcpf(1.0f + __builtin_amdgcn_exp2f(-1.4426950408889634f * v)); }
;     __device__ __forceinline__ void operator()(const pg8::f32x4 (&acc)[2][2][4][2], const pg8::Unit& u, int wr, int wc, int fr, int fq) const {
;     ...
;         for (int ai = 0; ai < 2; ++ai)
; #pragma unroll
;             for (int m = 0; m < 4; ++m) { const int row = row0 + ai * 128 + m * 16; const float rs = __builtin_amdgcn_rsqf(rsv[ai * 4 + m] * (1.0f / DM) + EPS); float o[8];
; #pragma unroll
;                 for (int n = 0; n < 2; ++n)
; #pragma unroll
;                     for (int e = 0; e < 4; ++e) { const float g = acc[ai][0][m][n][e] * rs, up = acc[ai][1][m][n][e] * rs; o[n * 4 + e] = g * fast_sigmoid(g) * up; }
;                 u32x4 w; w.x = cvt_pk(o[0], o[1]); w.y = cvt_pk(o[2], o[3]); w.z = cvt_pk(o[4], o[5]); w.w = cvt_pk(o[6], o[7]);
;                 *(u32x4*)(O + (size_t)row * ldc + col0) = w; }
	v_pk_mul_f32 v[96:97], v[96:97], v[100:101]
	v_pk_mul_f32 v[98:99], v[98:99], v[102:103]
	v_lshl_add_u64 v[152:153], v[152:153], 0, s[60:61]
	v_cvt_pk_bf16_f32 v108, v104, v105
	v_cvt_pk_bf16_f32 v109, v106, v107
	v_cvt_pk_bf16_f32 v110, v96, v97
	v_cvt_pk_bf16_f32 v111, v98, v99
	global_store_dwordx4 v[152:153], v[108:111], off
	v_pk_mul_f32 v[92:93], v[92:93], v[190:191] op_sel_hi:[1,0]
	v_pk_mul_f32 v[94:95], v[94:95], v[190:191] op_sel_hi:[1,0]
	v_pk_mul_f32 v[84:85], v[84:85], v[190:191] op_sel_hi:[1,0]
	v_pk_mul_f32 v[86:87], v[86:87], v[190:191] op_sel_hi:[1,0]
	v_exp_f32_e32 v92, v92
	v_exp_f32_e32 v93, v93
	v_exp_f32_e32 v94, v94
	v_exp_f32_e32 v95, v95
	v_exp_f32_e32 v84, v84
	v_exp_f32_e32 v85, v85
	v_exp_f32_e32 v86, v86
	v_exp_f32_e32 v87, v87
	v_pk_fma_f32 v[92:93], v[92:93], v[188:189], v[188:189] op_sel_hi:[1,0,0]
	v_pk_fma_f32 v[94:95], v[94:95], v[188:189], v[188:189] op_sel_hi:[1,0,0]
	v_pk_fma_f32 v[84:85], v[84:85], v[188:189], v[188:189] op_sel_hi:[1,0,0]
	v_pk_fma_f32 v[86:87], v[86:87], v[188:189], v[188:189] op_sel_hi:[1,0,0]
	v_rcp_f32_e32 v92, v92
	v_rcp_f32_e32 v93, v93
	v_rcp_f32_e32 v94, v94
	v_rcp_f32_e32 v95, v95
	v_rcp_f32_e32 v84, v84
	v_rcp_f32_e32 v85, v85
	v_rcp_f32_e32 v86, v86
	v_rcp_f32_e32 v87, v87
	v_pk_mul_f32 v[88:89], v[88:89], v[92:93]
	v_pk_mul_f32 v[90:91], v[90:91], v[94:95]
	v_pk_mul_f32 v[80:81], v[80:81], v[84:85]
	v_pk_mul_f32 v[82:83], v[82:83], v[86:87]
	v_lshl_add_u64 v[152:153], v[152:153], 0, s[60:61]
	v_cvt_pk_bf16_f32 v92, v88, v89
	v_cvt_pk_bf16_f32 v93, v90, v91
	v_cvt_pk_bf16_f32 v94, v80, v81
	v_cvt_pk_bf16_f32 v95, v82, v83
	global_store_dwordx4 v[152:153], v[92:95], off
	v_pk_mul_f32 v[76:77], v[76:77], v[194:195] op_sel_hi:[1,0]
	v_pk_mul_f32 v[78:79], v[78:79], v[194:195] op_sel_hi:[1,0]
	v_pk_mul_f32 v[68:69], v[68:69], v[194:195] op_sel_hi:[1,0]
	v_pk_mul_f32 v[70:71], v[70:71], v[194:195] op_sel_hi:[1,0]
	v_exp_f32_e32 v76, v76
	v_exp_f32_e32 v77, v77
	v_exp_f32_e32 v78, v78
	v_exp_f32_e32 v79, v79
	v_exp_f32_e32 v68, v68
	v_exp_f32_e32 v69, v69
	v_exp_f32_e32 v70, v70
	v_exp_f32_e32 v71, v71
	v_pk_fma_f32 v[76:77], v[76:77], v[192:193], v[192:193] op_sel_hi:[1,0,0]
	v_pk_fma_f32 v[78:79], v[78:79], v[192:193], v[192:193] op_sel_hi:[1,0,0]
	v_pk_fma_f32 v[68:69], v[68:69], v[192:193], v[192:193] op_sel_hi:[1,0,0]
	v_pk_fma_f32 v[70:71], v[70:71], v[192:193], v[192:193] op_sel_hi:[1,0,0]
	v_rcp_f32_e32 v76, v76
	v_rcp_f32_e32 v77, v77
	v_rcp_f32_e32 v78, v78
	v_rcp_f32_e32 v79, v79
	v_rcp_f32_e32 v68, v68
	v_rcp_f32_e32 v69, v69
	v_rcp_f32_e32 v70, v70
	v_rcp_f32_e32 v71, v71
	v_pk_mul_f32 v[72:73], v[72:73], v[76:77]
	v_pk_mul_f32 v[74:75], v[74:75], v[78:79]
	v_pk_mul_f32 v[64:65], v[64:65], v[68:69]
	v_pk_mul_f32 v[66:67], v[66:67], v[70:71]
	v_lshl_add_u64 v[152:153], v[152:153], 0, s[60:61]
	v_cvt_pk_bf16_f32 v76, v72, v73
	v_cvt_pk_bf16_f32 v77, v74, v75
	v_cvt_pk_bf16_f32 v78, v64, v65
	v_cvt_pk_bf16_f32 v79, v66, v67
	global_store_dwordx4 v[152:153], v[76:79], off
	v_pk_mul_f32 v[60:61], v[60:61], v[198:199] op_sel_hi:[1,0]
	v_pk_mul_f32 v[62:63], v[62:63], v[198:199] op_sel_hi:[1,0]
	v_pk_mul_f32 v[52:53], v[52:53], v[198:199] op_sel_hi:[1,0]
	v_pk_mul_f32 v[54:55], v[54:55], v[198:199] op_sel_hi:[1,0]
	v_exp_f32_e32 v60, v60
	v_exp_f32_e32 v61, v61
	v_exp_f32_e32 v62, v62
	v_exp_f32_e32 v63, v63
	v_exp_f32_e32 v52, v52
	v_exp_f32_e32 v53, v53
	v_exp_f32_e32 v54, v54
	v_exp_f32_e32 v55, v55
	v_pk_fma_f32 v[60:61], v[60:61], v[196:197], v[196:197] op_sel_hi:[1,0,0]
	v_pk_fma_f32 v[62:63], v[62:63], v[196:197], v[196:197] op_sel_hi:[1,0,0]
	v_pk_fma_f32 v[52:53], v[52:53], v[196:197], v[196:197] op_sel_hi:[1,0,0]
	v_pk_fma_f32 v[54:55], v[54:55], v[196:197], v[196:197] op_sel_hi:[1,0,0]
	v_rcp_f32_e32 v60, v60
	v_rcp_f32_e32 v61, v61
	v_rcp_f32_e32 v62, v62
	v_rcp_f32_e32 v63, v63
	v_rcp_f32_e32 v52, v52
	v_rcp_f32_e32 v53, v53
	v_rcp_f32_e32 v54, v54
	v_rcp_f32_e32 v55, v55
	v_pk_mul_f32 v[56:57], v[56:57], v[60:61]
	v_pk_mul_f32 v[58:59], v[58:59], v[62:63]
	v_pk_mul_f32 v[48:49], v[48:49], v[52:53]
	v_pk_mul_f32 v[50:51], v[50:51], v[54:55]
	v_lshl_add_u64 v[152:153], v[152:153], 0, s[62:63]
	v_cvt_pk_bf16_f32 v60, v56, v57
	v_cvt_pk_bf16_f32 v61, v58, v59
; __device__ __forceinline__ unsigned cvt_pk(float lo, float hi) { unsigned r; asm volatile("v_cvt_pk_bf16_f32 %0, %1, %2" : "=v"(r) : "v"(lo), "v"(hi)); return r; }
; __device__ __forceinline__ float fast_sigmoid(float v) { return __builtin_amdgcn_rcpf(1.0f + __builtin_amdgcn_exp2f(-1.4426950408889634f * v)); }
;     __device__ __forceinline__ void operator()(const pg8::f32x4 (&acc)[2][2][4][2], const pg8::Unit& u, int wr, int wc, int fr, int fq) const {
;     ...
;         for (int ai = 0; ai < 2; ++ai)
; #pragma unroll
;             for (int m = 0; m < 4; ++m) { const int row = row0 + ai * 128 + m * 16; const float rs = __builtin_amdgcn_rsqf(rsv[ai * 4 + m] * (1.0f / DM) + EPS); float o[8];
; #pragma unroll
;                 for (int n = 0; n < 2; ++n)
; #pragma unroll
;                     for (int e = 0; e < 4; ++e) { const float g = acc[ai][0][m][n][e] * rs, up = acc[ai][1][m][n][e] * rs; o[n * 4 + e] = g * fast_sigmoid(g) * up; }
;                 u32x4 w; w.x = cvt_pk(o[0], o[1]); w.y = cvt_pk(o[2], o[3]); w.z = cvt_pk(o[4], o[5]); w.w = cvt_pk(o[6], o[7]);
;                 *(u32x4*)(O + (size_t)row * ldc + col0) = w; }
	v_cvt_pk_bf16_f32 v62, v48, v49
	v_cvt_pk_bf16_f32 v63, v50, v51
	global_store_dwordx4 v[152:153], v[60:63], off
	v_pk_mul_f32 v[44:45], v[44:45], v[202:203] op_sel_hi:[1,0]
	v_pk_mul_f32 v[46:47], v[46:47], v[202:203] op_sel_hi:[1,0]
	v_pk_mul_f32 v[36:37], v[36:37], v[202:203] op_sel_hi:[1,0]
	v_pk_mul_f32 v[38:39], v[38:39], v[202:203] op_sel_hi:[1,0]
	v_exp_f32_e32 v44, v44
	v_exp_f32_e32 v45, v45
	v_exp_f32_e32 v46, v46
	v_exp_f32_e32 v47, v47
	v_exp_f32_e32 v36, v36
	v_exp_f32_e32 v37, v37
	v_exp_f32_e32 v38, v38
	v_exp_f32_e32 v39, v39
	v_pk_fma_f32 v[44:45], v[44:45], v[200:201], v[200:201] op_sel_hi:[1,0,0]
	v_pk_fma_f32 v[46:47], v[46:47], v[200:201], v[200:201] op_sel_hi:[1,0,0]
	v_pk_fma_f32 v[36:37], v[36:37], v[200:201], v[200:201] op_sel_hi:[1,0,0]
	v_pk_fma_f32 v[38:39], v[38:39], v[200:201], v[200:201] op_sel_hi:[1,0,0]
	v_rcp_f32_e32 v44, v44
	v_rcp_f32_e32 v45, v45
	v_rcp_f32_e32 v46, v46
	v_rcp_f32_e32 v47, v47
	v_rcp_f32_e32 v36, v36
	v_rcp_f32_e32 v37, v37
	v_rcp_f32_e32 v38, v38
	v_rcp_f32_e32 v39, v39
	v_pk_mul_f32 v[40:41], v[40:41], v[44:45]
	v_pk_mul_f32 v[42:43], v[42:43], v[46:47]
	v_pk_mul_f32 v[32:33], v[32:33], v[36:37]
	v_pk_mul_f32 v[34:35], v[34:35], v[38:39]
	v_lshl_add_u64 v[152:153], v[152:153], 0, s[60:61]
	v_cvt_pk_bf16_f32 v44, v40, v41
	v_cvt_pk_bf16_f32 v45, v42, v43
	v_cvt_pk_bf16_f32 v46, v32, v33
	v_cvt_pk_bf16_f32 v47, v34, v35
	global_store_dwordx4 v[152:153], v[44:47], off
	v_pk_mul_f32 v[28:29], v[28:29], v[206:207] op_sel_hi:[1,0]
	v_pk_mul_f32 v[30:31], v[30:31], v[206:207] op_sel_hi:[1,0]
	v_pk_mul_f32 v[20:21], v[20:21], v[206:207] op_sel_hi:[1,0]
	v_pk_mul_f32 v[22:23], v[22:23], v[206:207] op_sel_hi:[1,0]
	v_exp_f32_e32 v28, v28
	v_exp_f32_e32 v29, v29
	v_exp_f32_e32 v30, v30
	v_exp_f32_e32 v31, v31
	v_exp_f32_e32 v20, v20
	v_exp_f32_e32 v21, v21
	v_exp_f32_e32 v22, v22
	v_exp_f32_e32 v23, v23
	v_pk_fma_f32 v[28:29], v[28:29], v[204:205], v[204:205] op_sel_hi:[1,0,0]
	v_pk_fma_f32 v[30:31], v[30:31], v[204:205], v[204:205] op_sel_hi:[1,0,0]
	v_pk_fma_f32 v[20:21], v[20:21], v[204:205], v[204:205] op_sel_hi:[1,0,0]
	v_pk_fma_f32 v[22:23], v[22:23], v[204:205], v[204:205] op_sel_hi:[1,0,0]
	v_rcp_f32_e32 v28, v28
	v_rcp_f32_e32 v29, v29
	v_rcp_f32_e32 v30, v30
	v_rcp_f32_e32 v31, v31
	v_rcp_f32_e32 v20, v20
	v_rcp_f32_e32 v21, v21
	v_rcp_f32_e32 v22, v22
	v_rcp_f32_e32 v23, v23
	v_pk_mul_f32 v[24:25], v[24:25], v[28:29]
	v_pk_mul_f32 v[26:27], v[26:27], v[30:31]
	v_pk_mul_f32 v[16:17], v[16:17], v[20:21]
	v_pk_mul_f32 v[18:19], v[18:19], v[22:23]
	v_lshl_add_u64 v[152:153], v[152:153], 0, s[60:61]
	v_cvt_pk_bf16_f32 v28, v24, v25
	v_cvt_pk_bf16_f32 v29, v26, v27
	v_cvt_pk_bf16_f32 v30, v16, v17
	v_cvt_pk_bf16_f32 v31, v18, v19
	global_store_dwordx4 v[152:153], v[28:31], off
	v_pk_mul_f32 v[12:13], v[12:13], v[210:211] op_sel_hi:[1,0]
	v_pk_mul_f32 v[14:15], v[14:15], v[210:211] op_sel_hi:[1,0]
	v_pk_mul_f32 v[4:5], v[4:5], v[210:211] op_sel_hi:[1,0]
	v_pk_mul_f32 v[6:7], v[6:7], v[210:211] op_sel_hi:[1,0]
	v_exp_f32_e32 v12, v12
	v_exp_f32_e32 v13, v13
	v_exp_f32_e32 v14, v14
	v_exp_f32_e32 v15, v15
	v_exp_f32_e32 v4, v4
	v_exp_f32_e32 v5, v5
	v_exp_f32_e32 v6, v6
	v_exp_f32_e32 v7, v7
	v_pk_fma_f32 v[12:13], v[12:13], v[208:209], v[208:209] op_sel_hi:[1,0,0]
	v_pk_fma_f32 v[14:15], v[14:15], v[208:209], v[208:209] op_sel_hi:[1,0,0]
	v_pk_fma_f32 v[4:5], v[4:5], v[208:209], v[208:209] op_sel_hi:[1,0,0]
	v_pk_fma_f32 v[6:7], v[6:7], v[208:209], v[208:209] op_sel_hi:[1,0,0]
	v_rcp_f32_e32 v12, v12
	v_rcp_f32_e32 v13, v13
	v_rcp_f32_e32 v14, v14
	v_rcp_f32_e32 v15, v15
	v_rcp_f32_e32 v4, v4
	v_rcp_f32_e32 v5, v5
	v_rcp_f32_e32 v6, v6
	v_rcp_f32_e32 v7, v7
	v_pk_mul_f32 v[8:9], v[8:9], v[12:13]
	v_pk_mul_f32 v[10:11], v[10:11], v[14:15]
	v_pk_mul_f32 v[0:1], v[0:1], v[4:5]
	v_pk_mul_f32 v[2:3], v[2:3], v[6:7]
	v_lshl_add_u64 v[152:153], v[152:153], 0, s[60:61]
	v_cvt_pk_bf16_f32 v12, v8, v9
	v_cvt_pk_bf16_f32 v13, v10, v11
	v_cvt_pk_bf16_f32 v14, v0, v1
	v_cvt_pk_bf16_f32 v15, v2, v3
	global_store_dwordx4 v[152:153], v[12:15], off
	s_andn2_b64 vcc, exec, s[4:5]
	s_mov_b64 s[4:5], -1
	s_cbranch_vccnz .LBB0_662
	s_andn2_b64 vcc, exec, s[6:7]
	s_cbranch_vccnz .LBB0_661
	s_barrier
	s_branch .LBB0_661
